# FFN1 epilogue rewritten by hand: DPP-fused conv (v_fmac_f32_dpp row_shr/row_shl with bound_ctrl + masked-weight row_ror for block edges), packed f32 silu, weights loaded once per unit; on top of ATT_B
# speedup vs baseline: 1.0144x; 1.0082x over previous
;     __device__ __forceinline__ void operator()(const f32x4 (&acc)[2][2][4][2], const pg8::Unit& u, int wr, int wc, int fr, int fq) const {
;     ...
;             bf16_t* U = (bf16_t*)(ws + RF_U); float* EDGE = (float*)(ws + RF_EDGE);
; #pragma unroll
;             for (int ai = 0; ai < 2; ++ai) {
;                 const int chunk = u.pm * 4 + ai * 2 + wr;
;                 const int cseq = lat ? (chunk & 63) : ((chunk - MLAT / 64) & 3);
;                 const bool seq_first = cseq == 0, seq_last = lat ? (cseq == 63) : (cseq == 3);
;                 const int fb = u.pn * 128 + wc * 32 + 8 * fq;
;                 u32x2 uw0[4];
; #pragma unroll
;                 for (int n = 0; n < 2; ++n) {
;                     const int f0 = fb + 4 * n;
;                     const f32x4 w0 = *(const f32x4*)(cw + f0), w1 = *(const f32x4*)(cw + DFF + f0), w2 = *(const f32x4*)(cw + 2 * DFF + f0), bb = *(const f32x4*)(cb + f0);
;                     f32x4 pre[4];
; #pragma unroll
;                     for (int j = 0; j < 4; ++j) {
;                         float t[4], up[4], dn[4];
; #pragma unroll
;                         for (int m = 0; m < 4; ++m) { t[m] = acc[ai][0][m][n][j];
;                             up[m] = __builtin_bit_cast(float, __builtin_amdgcn_update_dpp(0, __builtin_bit_cast(int, t[m]), 0x121, 0xf, 0xf, false));
;                             dn[m] = __builtin_bit_cast(float, __builtin_amdgcn_update_dpp(0, __builtin_bit_cast(int, t[m]), 0x12F, 0xf, 0xf, false)); }
; #pragma unroll
;                         for (int m = 0; m < 4; ++m) {
;                             const float pv = (fr == 0) ? (m > 0 ? up[m > 0 ? m - 1 : 0] : 0.f) : up[m];
;                             const float nx = (fr == 15) ? (m < 3 ? dn[m < 3 ? m + 1 : 3] : 0.f) : dn[m];
;                             pre[m][j] = w0[j] * pv + w1[j] * t[m] + w2[j] * nx + bb[j];
.LBB0_700:
	s_mov_b64 s[56:57], exec
	v_readlane_b32 s28, v253, 49
	v_readlane_b32 s29, v253, 50
	v_readlane_b32 s30, v250, 23
	v_readlane_b32 s31, v250, 24
	v_readlane_b32 s0, v250, 32
	v_lshl_add_u32 v202, s84, 7, v206
	v_lshlrev_b32_e32 v202, 2, v202
	v_add_u32_e32 v203, 16, v202
	v_cmp_eq_u32_e64 s[42:43], 0, v5
	v_cmp_eq_u32_e64 s[40:41], 15, v5
	v_add_u32_e32 v204, s50, v188
	v_mul_u32_u24_e32 v204, 0x1600, v204
	v_lshrrev_b32_e32 v0, 1, v202
	v_add_u32_e32 v204, v204, v0
	s_nop 4
	global_load_dwordx4 v[142:145], v202, s[28:29]
	global_load_dwordx4 v[222:225], v203, s[28:29]
	global_load_dwordx4 v[154:157], v202, s[30:31]
	global_load_dwordx4 v[234:237], v203, s[30:31]
	s_add_u32 s28, s28, 0x2c00
	s_addc_u32 s29, s29, 0
	global_load_dwordx4 v[146:149], v202, s[28:29]
	global_load_dwordx4 v[226:229], v203, s[28:29]
	s_add_u32 s28, s28, 0x2c00
	s_addc_u32 s29, s29, 0
	global_load_dwordx4 v[150:153], v202, s[28:29]
	global_load_dwordx4 v[230:233], v203, s[28:29]
	s_lshl_b32 s51, s66, 2
	s_add_i32 s51, s51, s0
	s_cmp_lt_i32 s66, 0x80
	s_cselect_b32 s25, 63, 3
	v_readlane_b32 s44, v250, 45
	v_readlane_b32 s45, v250, 46
	v_readlane_b32 s66, v250, 49
	v_readlane_b32 s67, v250, 50
	s_mov_b32 s28, 0xbfb8aa3b
	s_waitcnt vmcnt(0)
	v_cndmask_b32_e64 v158, 0, v142, s[42:43]
	v_cndmask_b32_e64 v159, 0, v143, s[42:43]
	v_cndmask_b32_e64 v160, 0, v144, s[42:43]
	v_cndmask_b32_e64 v161, 0, v145, s[42:43]
	v_cndmask_b32_e64 v162, 0, v150, s[40:41]
	v_cndmask_b32_e64 v163, 0, v151, s[40:41]
	v_cndmask_b32_e64 v164, 0, v152, s[40:41]
	v_cndmask_b32_e64 v165, 0, v153, s[40:41]
	v_cndmask_b32_e64 v238, 0, v222, s[42:43]
	v_cndmask_b32_e64 v239, 0, v223, s[42:43]
	v_cndmask_b32_e64 v240, 0, v224, s[42:43]
	v_cndmask_b32_e64 v241, 0, v225, s[42:43]
	v_cndmask_b32_e64 v198, 0, v230, s[40:41]
	v_cndmask_b32_e64 v199, 0, v231, s[40:41]
	v_cndmask_b32_e64 v200, 0, v232, s[40:41]
	v_cndmask_b32_e64 v201, 0, v233, s[40:41]
	s_add_i32 s1, s51, 0
	s_and_b32 s0, s1, s25
	s_cmp_lg_u32 s0, 0
	s_cselect_b32 s27, 1, 0
	s_cmp_lg_u32 s0, s25
	s_cselect_b32 s0, 2, 0
	s_or_b32 s27, s27, s0
	s_lshl_b32 s1, s1, 1
	s_mul_i32 s1, s1, 0x8400
	s_add_u32 s30, s66, s1
	s_addc_u32 s31, s67, 0
	v_pk_fma_f32 v[166:167], v[146:147], v[138:139], v[154:155]
	v_pk_fma_f32 v[168:169], v[148:149], v[140:141], v[156:157]
	v_pk_fma_f32 v[170:171], v[146:147], v[130:131], v[154:155]
	v_pk_fma_f32 v[172:173], v[148:149], v[132:133], v[156:157]
	v_pk_fma_f32 v[174:175], v[146:147], v[118:119], v[154:155]
	v_pk_fma_f32 v[176:177], v[148:149], v[120:121], v[156:157]
	v_pk_fma_f32 v[178:179], v[146:147], v[102:103], v[154:155]
	v_pk_fma_f32 v[180:181], v[148:149], v[104:105], v[156:157]
	v_fmac_f32_dpp v166, v138, v142 row_shr:1 row_mask:0xf bank_mask:0xf bound_ctrl:0
	v_fmac_f32_dpp v167, v139, v143 row_shr:1 row_mask:0xf bank_mask:0xf bound_ctrl:0
	v_fmac_f32_dpp v168, v140, v144 row_shr:1 row_mask:0xf bank_mask:0xf bound_ctrl:0
	v_fmac_f32_dpp v169, v141, v145 row_shr:1 row_mask:0xf bank_mask:0xf bound_ctrl:0
	v_fmac_f32_dpp v170, v130, v142 row_shr:1 row_mask:0xf bank_mask:0xf bound_ctrl:0
	v_fmac_f32_dpp v171, v131, v143 row_shr:1 row_mask:0xf bank_mask:0xf bound_ctrl:0
	v_fmac_f32_dpp v172, v132, v144 row_shr:1 row_mask:0xf bank_mask:0xf bound_ctrl:0
	v_fmac_f32_dpp v173, v133, v145 row_shr:1 row_mask:0xf bank_mask:0xf bound_ctrl:0
	v_fmac_f32_dpp v174, v118, v142 row_shr:1 row_mask:0xf bank_mask:0xf bound_ctrl:0
	v_fmac_f32_dpp v175, v119, v143 row_shr:1 row_mask:0xf bank_mask:0xf bound_ctrl:0
	v_fmac_f32_dpp v176, v120, v144 row_shr:1 row_mask:0xf bank_mask:0xf bound_ctrl:0
	v_fmac_f32_dpp v177, v121, v145 row_shr:1 row_mask:0xf bank_mask:0xf bound_ctrl:0
	v_fmac_f32_dpp v178, v102, v142 row_shr:1 row_mask:0xf bank_mask:0xf bound_ctrl:0
	v_fmac_f32_dpp v179, v103, v143 row_shr:1 row_mask:0xf bank_mask:0xf bound_ctrl:0
	v_fmac_f32_dpp v180, v104, v144 row_shr:1 row_mask:0xf bank_mask:0xf bound_ctrl:0
	v_fmac_f32_dpp v181, v105, v145 row_shr:1 row_mask:0xf bank_mask:0xf bound_ctrl:0
	v_fmac_f32_dpp v170, v138, v158 row_ror:1 row_mask:0xf bank_mask:0xf
	v_fmac_f32_dpp v171, v139, v159 row_ror:1 row_mask:0xf bank_mask:0xf
	v_fmac_f32_dpp v172, v140, v160 row_ror:1 row_mask:0xf bank_mask:0xf
	v_fmac_f32_dpp v173, v141, v161 row_ror:1 row_mask:0xf bank_mask:0xf
	v_fmac_f32_dpp v174, v130, v158 row_ror:1 row_mask:0xf bank_mask:0xf
	v_fmac_f32_dpp v175, v131, v159 row_ror:1 row_mask:0xf bank_mask:0xf
	v_fmac_f32_dpp v176, v132, v160 row_ror:1 row_mask:0xf bank_mask:0xf
	v_fmac_f32_dpp v177, v133, v161 row_ror:1 row_mask:0xf bank_mask:0xf
	v_fmac_f32_dpp v178, v118, v158 row_ror:1 row_mask:0xf bank_mask:0xf
	v_fmac_f32_dpp v179, v119, v159 row_ror:1 row_mask:0xf bank_mask:0xf
	v_fmac_f32_dpp v180, v120, v160 row_ror:1 row_mask:0xf bank_mask:0xf
	v_fmac_f32_dpp v181, v121, v161 row_ror:1 row_mask:0xf bank_mask:0xf
	v_fmac_f32_dpp v166, v138, v150 row_shl:1 row_mask:0xf bank_mask:0xf bound_ctrl:0
	v_fmac_f32_dpp v167, v139, v151 row_shl:1 row_mask:0xf bank_mask:0xf bound_ctrl:0
	v_fmac_f32_dpp v168, v140, v152 row_shl:1 row_mask:0xf bank_mask:0xf bound_ctrl:0
	v_fmac_f32_dpp v169, v141, v153 row_shl:1 row_mask:0xf bank_mask:0xf bound_ctrl:0
	v_fmac_f32_dpp v170, v130, v150 row_shl:1 row_mask:0xf bank_mask:0xf bound_ctrl:0
	v_fmac_f32_dpp v171, v131, v151 row_shl:1 row_mask:0xf bank_mask:0xf bound_ctrl:0
	v_fmac_f32_dpp v172, v132, v152 row_shl:1 row_mask:0xf bank_mask:0xf bound_ctrl:0
	v_fmac_f32_dpp v173, v133, v153 row_shl:1 row_mask:0xf bank_mask:0xf bound_ctrl:0
	v_fmac_f32_dpp v174, v118, v150 row_shl:1 row_mask:0xf bank_mask:0xf bound_ctrl:0
	v_fmac_f32_dpp v175, v119, v151 row_shl:1 row_mask:0xf bank_mask:0xf bound_ctrl:0
; __device__ __forceinline__ unsigned cvt_pk_bf16(float lo, float hi) { unsigned r; asm volatile("v_cvt_pk_bf16_f32 %0, %1, %2" : "=v"(r) : "v"(lo), "v"(hi)); return r; }
; __device__ __forceinline__ float silu_f(float a) { return a * __builtin_amdgcn_rcpf(1.0f + __expf(-a)); }
;     __device__ __forceinline__ void operator()(const f32x4 (&acc)[2][2][4][2], const pg8::Unit& u, int wr, int wc, int fr, int fq) const {
;     ...
;                         for (int m = 0; m < 4; ++m) {
;                             const float pv = (fr == 0) ? (m > 0 ? up[m > 0 ? m - 1 : 0] : 0.f) : up[m];
;                             const float nx = (fr == 15) ? (m < 3 ? dn[m < 3 ? m + 1 : 3] : 0.f) : dn[m];
;                             pre[m][j] = w0[j] * pv + w1[j] * t[m] + w2[j] * nx + bb[j];
;                         }
;                     }
; #pragma unroll
;                     for (int m = 0; m < 4; ++m) {
;                         const bool top = (m == 0 && fr == 0), bot = (m == 3 && fr == 15);
;                         const bool need_fix = (top && !seq_first) || (bot && !seq_last);
;                         const f32x4 vv = acc[ai][1][m][n];
;                         if (top || bot) {
;                             float* e = EDGE + ((size_t)(chunk * 2 + (bot ? 1 : 0)) * 3) * DFF + f0;
;                             *(f32x4*)e = acc[ai][0][m][n];
;                             if (need_fix) { *(f32x4*)(e + DFF) = pre[m]; *(f32x4*)(e + 2 * DFF) = vv; }
;                         }
;                         u32x2 w; w.x = cvt_pk_bf16(silu_f(pre[m][0]) * vv[0], silu_f(pre[m][1]) * vv[1]); w.y = cvt_pk_bf16(silu_f(pre[m][2]) * vv[2], silu_f(pre[m][3]) * vv[3]);
;                         if (n == 0) uw0[m] = w;
;                         else if (!need_fix) { const int row = rowt + lane_r + ai * 128 + m * 16; *(u32x4*)(U + (size_t)row * DFF + fb) = (u32x4){uw0[m].x, uw0[m].y, w.x, w.y}; }
	v_fmac_f32_dpp v176, v120, v152 row_shl:1 row_mask:0xf bank_mask:0xf bound_ctrl:0
	v_fmac_f32_dpp v177, v121, v153 row_shl:1 row_mask:0xf bank_mask:0xf bound_ctrl:0
	v_fmac_f32_dpp v178, v102, v150 row_shl:1 row_mask:0xf bank_mask:0xf bound_ctrl:0
	v_fmac_f32_dpp v179, v103, v151 row_shl:1 row_mask:0xf bank_mask:0xf bound_ctrl:0
	v_fmac_f32_dpp v180, v104, v152 row_shl:1 row_mask:0xf bank_mask:0xf bound_ctrl:0
	v_fmac_f32_dpp v181, v105, v153 row_shl:1 row_mask:0xf bank_mask:0xf bound_ctrl:0
	v_fmac_f32_dpp v166, v130, v162 row_ror:15 row_mask:0xf bank_mask:0xf
	v_fmac_f32_dpp v167, v131, v163 row_ror:15 row_mask:0xf bank_mask:0xf
	v_fmac_f32_dpp v168, v132, v164 row_ror:15 row_mask:0xf bank_mask:0xf
	v_fmac_f32_dpp v169, v133, v165 row_ror:15 row_mask:0xf bank_mask:0xf
	v_fmac_f32_dpp v170, v118, v162 row_ror:15 row_mask:0xf bank_mask:0xf
	v_fmac_f32_dpp v171, v119, v163 row_ror:15 row_mask:0xf bank_mask:0xf
	v_fmac_f32_dpp v172, v120, v164 row_ror:15 row_mask:0xf bank_mask:0xf
	v_fmac_f32_dpp v173, v121, v165 row_ror:15 row_mask:0xf bank_mask:0xf
	v_fmac_f32_dpp v174, v102, v162 row_ror:15 row_mask:0xf bank_mask:0xf
	v_fmac_f32_dpp v175, v103, v163 row_ror:15 row_mask:0xf bank_mask:0xf
	v_fmac_f32_dpp v176, v104, v164 row_ror:15 row_mask:0xf bank_mask:0xf
	v_fmac_f32_dpp v177, v105, v165 row_ror:15 row_mask:0xf bank_mask:0xf
	s_mov_b64 exec, s[42:43]
	global_store_dwordx4 v202, v[138:141], s[30:31]
	s_bitcmp1_b32 s27, 0
	s_cbranch_scc0 .Lmy_f1_t00
	s_add_u32 s0, s30, 0x2c00
	s_addc_u32 s1, s31, 0
	global_store_dwordx4 v202, v[166:169], s[0:1]
	s_add_u32 s0, s0, 0x2c00
	s_addc_u32 s1, s1, 0
	global_store_dwordx4 v202, v[122:125], s[0:1]
.Lmy_f1_t00:
	s_mov_b64 exec, s[40:41]
	s_add_u32 s0, s30, 0x8400
	s_addc_u32 s1, s31, 0
	global_store_dwordx4 v202, v[102:105], s[0:1]
	s_bitcmp1_b32 s27, 1
	s_cbranch_scc0 .Lmy_f1_b00
	s_add_u32 s0, s0, 0x2c00
	s_addc_u32 s1, s1, 0
	global_store_dwordx4 v202, v[178:181], s[0:1]
	s_add_u32 s0, s0, 0x2c00
	s_addc_u32 s1, s1, 0
	global_store_dwordx4 v202, v[82:85], s[0:1]
.Lmy_f1_b00:
	s_mov_b64 exec, s[56:57]
	s_nop 1
	v_pk_mul_f32 v[138:139], v[166:167], s[28:29] op_sel_hi:[1,0]
	v_pk_mul_f32 v[140:141], v[168:169], s[28:29] op_sel_hi:[1,0]
	v_pk_mul_f32 v[130:131], v[170:171], s[28:29] op_sel_hi:[1,0]
	v_pk_mul_f32 v[132:133], v[172:173], s[28:29] op_sel_hi:[1,0]
	v_pk_mul_f32 v[118:119], v[174:175], s[28:29] op_sel_hi:[1,0]
	v_pk_mul_f32 v[120:121], v[176:177], s[28:29] op_sel_hi:[1,0]
	v_pk_mul_f32 v[102:103], v[178:179], s[28:29] op_sel_hi:[1,0]
	v_pk_mul_f32 v[104:105], v[180:181], s[28:29] op_sel_hi:[1,0]
	v_exp_f32_e32 v138, v138
	v_exp_f32_e32 v139, v139
	v_exp_f32_e32 v140, v140
	v_exp_f32_e32 v141, v141
	v_exp_f32_e32 v130, v130
	v_exp_f32_e32 v131, v131
	v_exp_f32_e32 v132, v132
	v_exp_f32_e32 v133, v133
	v_exp_f32_e32 v118, v118
	v_exp_f32_e32 v119, v119
	v_exp_f32_e32 v120, v120
	v_exp_f32_e32 v121, v121
	v_exp_f32_e32 v102, v102
	v_exp_f32_e32 v103, v103
	v_exp_f32_e32 v104, v104
	v_exp_f32_e32 v105, v105
	v_pk_add_f32 v[138:139], v[138:139], 1.0 op_sel_hi:[1,0]
	v_pk_add_f32 v[140:141], v[140:141], 1.0 op_sel_hi:[1,0]
	v_pk_add_f32 v[130:131], v[130:131], 1.0 op_sel_hi:[1,0]
	v_pk_add_f32 v[132:133], v[132:133], 1.0 op_sel_hi:[1,0]
	v_pk_add_f32 v[118:119], v[118:119], 1.0 op_sel_hi:[1,0]
	v_pk_add_f32 v[120:121], v[120:121], 1.0 op_sel_hi:[1,0]
	v_pk_add_f32 v[102:103], v[102:103], 1.0 op_sel_hi:[1,0]
	v_pk_add_f32 v[104:105], v[104:105], 1.0 op_sel_hi:[1,0]
	v_rcp_f32_e32 v138, v138
	v_rcp_f32_e32 v139, v139
	v_rcp_f32_e32 v140, v140
	v_rcp_f32_e32 v141, v141
	v_rcp_f32_e32 v130, v130
	v_rcp_f32_e32 v131, v131
	v_rcp_f32_e32 v132, v132
	v_rcp_f32_e32 v133, v133
	v_rcp_f32_e32 v118, v118
	v_rcp_f32_e32 v119, v119
	v_rcp_f32_e32 v120, v120
	v_rcp_f32_e32 v121, v121
	v_rcp_f32_e32 v102, v102
	v_rcp_f32_e32 v103, v103
	v_rcp_f32_e32 v104, v104
	v_rcp_f32_e32 v105, v105
	v_pk_mul_f32 v[166:167], v[166:167], v[138:139]
	v_pk_mul_f32 v[168:169], v[168:169], v[140:141]
	v_pk_mul_f32 v[170:171], v[170:171], v[130:131]
	v_pk_mul_f32 v[172:173], v[172:173], v[132:133]
	v_pk_mul_f32 v[174:175], v[174:175], v[118:119]
	v_pk_mul_f32 v[176:177], v[176:177], v[120:121]
	v_pk_mul_f32 v[178:179], v[178:179], v[102:103]
	v_pk_mul_f32 v[180:181], v[180:181], v[104:105]
	v_pk_mul_f32 v[166:167], v[122:123], v[166:167]
	v_pk_mul_f32 v[168:169], v[124:125], v[168:169]
	v_pk_mul_f32 v[170:171], v[106:107], v[170:171]
	v_pk_mul_f32 v[172:173], v[108:109], v[172:173]
	v_pk_mul_f32 v[174:175], v[90:91], v[174:175]
	v_pk_mul_f32 v[176:177], v[92:93], v[176:177]
	v_pk_mul_f32 v[178:179], v[82:83], v[178:179]
	v_pk_mul_f32 v[180:181], v[84:85], v[180:181]
	v_cvt_pk_bf16_f32 v122, v166, v167
	v_cvt_pk_bf16_f32 v123, v168, v169
	v_cvt_pk_bf16_f32 v106, v170, v171
	v_cvt_pk_bf16_f32 v107, v172, v173
	v_cvt_pk_bf16_f32 v90, v174, v175
	v_cvt_pk_bf16_f32 v91, v176, v177
	v_cvt_pk_bf16_f32 v82, v178, v179
	v_cvt_pk_bf16_f32 v83, v180, v181
	v_pk_fma_f32 v[166:167], v[226:227], v[134:135], v[234:235]
	v_pk_fma_f32 v[168:169], v[228:229], v[136:137], v[236:237]
	v_pk_fma_f32 v[170:171], v[226:227], v[126:127], v[234:235]
	v_pk_fma_f32 v[172:173], v[228:229], v[128:129], v[236:237]
	v_pk_fma_f32 v[174:175], v[226:227], v[110:111], v[234:235]
	v_pk_fma_f32 v[176:177], v[228:229], v[112:113], v[236:237]
	v_pk_fma_f32 v[178:179], v[226:227], v[94:95], v[234:235]
	v_pk_fma_f32 v[180:181], v[228:229], v[96:97], v[236:237]
	v_fmac_f32_dpp v166, v134, v222 row_shr:1 row_mask:0xf bank_mask:0xf bound_ctrl:0
	v_fmac_f32_dpp v167, v135, v223 row_shr:1 row_mask:0xf bank_mask:0xf bound_ctrl:0
;     __device__ __forceinline__ void operator()(const f32x4 (&acc)[2][2][4][2], const pg8::Unit& u, int wr, int wc, int fr, int fq) const {
;     ...
;                     for (int j = 0; j < 4; ++j) {
;                         float t[4], up[4], dn[4];
; #pragma unroll
;                         for (int m = 0; m < 4; ++m) { t[m] = acc[ai][0][m][n][j];
;                             up[m] = __builtin_bit_cast(float, __builtin_amdgcn_update_dpp(0, __builtin_bit_cast(int, t[m]), 0x121, 0xf, 0xf, false));
;                             dn[m] = __builtin_bit_cast(float, __builtin_amdgcn_update_dpp(0, __builtin_bit_cast(int, t[m]), 0x12F, 0xf, 0xf, false)); }
; #pragma unroll
;                         for (int m = 0; m < 4; ++m) {
;                             const float pv = (fr == 0) ? (m > 0 ? up[m > 0 ? m - 1 : 0] : 0.f) : up[m];
;                             const float nx = (fr == 15) ? (m < 3 ? dn[m < 3 ? m + 1 : 3] : 0.f) : dn[m];
;                             pre[m][j] = w0[j] * pv + w1[j] * t[m] + w2[j] * nx + bb[j];
;                         }
;                     }
; #pragma unroll
;                     for (int m = 0; m < 4; ++m) {
;                         const bool top = (m == 0 && fr == 0), bot = (m == 3 && fr == 15);
;                         const bool need_fix = (top && !seq_first) || (bot && !seq_last);
;                         const f32x4 vv = acc[ai][1][m][n];
;                         if (top || bot) {
;                             float* e = EDGE + ((size_t)(chunk * 2 + (bot ? 1 : 0)) * 3) * DFF + f0;
;                             *(f32x4*)e = acc[ai][0][m][n];
;                             if (need_fix) { *(f32x4*)(e + DFF) = pre[m]; *(f32x4*)(e + 2 * DFF) = vv; }
;                         }
	v_fmac_f32_dpp v168, v136, v224 row_shr:1 row_mask:0xf bank_mask:0xf bound_ctrl:0
	v_fmac_f32_dpp v169, v137, v225 row_shr:1 row_mask:0xf bank_mask:0xf bound_ctrl:0
	v_fmac_f32_dpp v170, v126, v222 row_shr:1 row_mask:0xf bank_mask:0xf bound_ctrl:0
	v_fmac_f32_dpp v171, v127, v223 row_shr:1 row_mask:0xf bank_mask:0xf bound_ctrl:0
	v_fmac_f32_dpp v172, v128, v224 row_shr:1 row_mask:0xf bank_mask:0xf bound_ctrl:0
	v_fmac_f32_dpp v173, v129, v225 row_shr:1 row_mask:0xf bank_mask:0xf bound_ctrl:0
	v_fmac_f32_dpp v174, v110, v222 row_shr:1 row_mask:0xf bank_mask:0xf bound_ctrl:0
	v_fmac_f32_dpp v175, v111, v223 row_shr:1 row_mask:0xf bank_mask:0xf bound_ctrl:0
	v_fmac_f32_dpp v176, v112, v224 row_shr:1 row_mask:0xf bank_mask:0xf bound_ctrl:0
	v_fmac_f32_dpp v177, v113, v225 row_shr:1 row_mask:0xf bank_mask:0xf bound_ctrl:0
	v_fmac_f32_dpp v178, v94, v222 row_shr:1 row_mask:0xf bank_mask:0xf bound_ctrl:0
	v_fmac_f32_dpp v179, v95, v223 row_shr:1 row_mask:0xf bank_mask:0xf bound_ctrl:0
	v_fmac_f32_dpp v180, v96, v224 row_shr:1 row_mask:0xf bank_mask:0xf bound_ctrl:0
	v_fmac_f32_dpp v181, v97, v225 row_shr:1 row_mask:0xf bank_mask:0xf bound_ctrl:0
	v_fmac_f32_dpp v170, v134, v238 row_ror:1 row_mask:0xf bank_mask:0xf
	v_fmac_f32_dpp v171, v135, v239 row_ror:1 row_mask:0xf bank_mask:0xf
	v_fmac_f32_dpp v172, v136, v240 row_ror:1 row_mask:0xf bank_mask:0xf
	v_fmac_f32_dpp v173, v137, v241 row_ror:1 row_mask:0xf bank_mask:0xf
	v_fmac_f32_dpp v174, v126, v238 row_ror:1 row_mask:0xf bank_mask:0xf
	v_fmac_f32_dpp v175, v127, v239 row_ror:1 row_mask:0xf bank_mask:0xf
	v_fmac_f32_dpp v176, v128, v240 row_ror:1 row_mask:0xf bank_mask:0xf
	v_fmac_f32_dpp v177, v129, v241 row_ror:1 row_mask:0xf bank_mask:0xf
	v_fmac_f32_dpp v178, v110, v238 row_ror:1 row_mask:0xf bank_mask:0xf
	v_fmac_f32_dpp v179, v111, v239 row_ror:1 row_mask:0xf bank_mask:0xf
	v_fmac_f32_dpp v180, v112, v240 row_ror:1 row_mask:0xf bank_mask:0xf
	v_fmac_f32_dpp v181, v113, v241 row_ror:1 row_mask:0xf bank_mask:0xf
	v_fmac_f32_dpp v166, v134, v230 row_shl:1 row_mask:0xf bank_mask:0xf bound_ctrl:0
	v_fmac_f32_dpp v167, v135, v231 row_shl:1 row_mask:0xf bank_mask:0xf bound_ctrl:0
	v_fmac_f32_dpp v168, v136, v232 row_shl:1 row_mask:0xf bank_mask:0xf bound_ctrl:0
	v_fmac_f32_dpp v169, v137, v233 row_shl:1 row_mask:0xf bank_mask:0xf bound_ctrl:0
	v_fmac_f32_dpp v170, v126, v230 row_shl:1 row_mask:0xf bank_mask:0xf bound_ctrl:0
	v_fmac_f32_dpp v171, v127, v231 row_shl:1 row_mask:0xf bank_mask:0xf bound_ctrl:0
	v_fmac_f32_dpp v172, v128, v232 row_shl:1 row_mask:0xf bank_mask:0xf bound_ctrl:0
	v_fmac_f32_dpp v173, v129, v233 row_shl:1 row_mask:0xf bank_mask:0xf bound_ctrl:0
	v_fmac_f32_dpp v174, v110, v230 row_shl:1 row_mask:0xf bank_mask:0xf bound_ctrl:0
	v_fmac_f32_dpp v175, v111, v231 row_shl:1 row_mask:0xf bank_mask:0xf bound_ctrl:0
	v_fmac_f32_dpp v176, v112, v232 row_shl:1 row_mask:0xf bank_mask:0xf bound_ctrl:0
	v_fmac_f32_dpp v177, v113, v233 row_shl:1 row_mask:0xf bank_mask:0xf bound_ctrl:0
	v_fmac_f32_dpp v178, v94, v230 row_shl:1 row_mask:0xf bank_mask:0xf bound_ctrl:0
	v_fmac_f32_dpp v179, v95, v231 row_shl:1 row_mask:0xf bank_mask:0xf bound_ctrl:0
	v_fmac_f32_dpp v180, v96, v232 row_shl:1 row_mask:0xf bank_mask:0xf bound_ctrl:0
	v_fmac_f32_dpp v181, v97, v233 row_shl:1 row_mask:0xf bank_mask:0xf bound_ctrl:0
	v_fmac_f32_dpp v166, v126, v198 row_ror:15 row_mask:0xf bank_mask:0xf
	v_fmac_f32_dpp v167, v127, v199 row_ror:15 row_mask:0xf bank_mask:0xf
	v_fmac_f32_dpp v168, v128, v200 row_ror:15 row_mask:0xf bank_mask:0xf
	v_fmac_f32_dpp v169, v129, v201 row_ror:15 row_mask:0xf bank_mask:0xf
	v_fmac_f32_dpp v170, v110, v198 row_ror:15 row_mask:0xf bank_mask:0xf
	v_fmac_f32_dpp v171, v111, v199 row_ror:15 row_mask:0xf bank_mask:0xf
	v_fmac_f32_dpp v172, v112, v200 row_ror:15 row_mask:0xf bank_mask:0xf
	v_fmac_f32_dpp v173, v113, v201 row_ror:15 row_mask:0xf bank_mask:0xf
	v_fmac_f32_dpp v174, v94, v198 row_ror:15 row_mask:0xf bank_mask:0xf
	v_fmac_f32_dpp v175, v95, v199 row_ror:15 row_mask:0xf bank_mask:0xf
	v_fmac_f32_dpp v176, v96, v200 row_ror:15 row_mask:0xf bank_mask:0xf
	v_fmac_f32_dpp v177, v97, v201 row_ror:15 row_mask:0xf bank_mask:0xf
	s_mov_b64 exec, s[42:43]
	global_store_dwordx4 v203, v[134:137], s[30:31]
	s_bitcmp1_b32 s27, 0
	s_cbranch_scc0 .Lmy_f1_t01
	s_add_u32 s0, s30, 0x2c00
	s_addc_u32 s1, s31, 0
	global_store_dwordx4 v203, v[166:169], s[0:1]
	s_add_u32 s0, s0, 0x2c00
	s_addc_u32 s1, s1, 0
	global_store_dwordx4 v203, v[114:117], s[0:1]
.Lmy_f1_t01:
	s_mov_b64 exec, s[40:41]
	s_add_u32 s0, s30, 0x8400
	s_addc_u32 s1, s31, 0
	global_store_dwordx4 v203, v[94:97], s[0:1]
	s_bitcmp1_b32 s27, 1
	s_cbranch_scc0 .Lmy_f1_b01
	s_add_u32 s0, s0, 0x2c00
	s_addc_u32 s1, s1, 0
	global_store_dwordx4 v203, v[178:181], s[0:1]
	s_add_u32 s0, s0, 0x2c00
	s_addc_u32 s1, s1, 0
	global_store_dwordx4 v203, v[78:81], s[0:1]
; __device__ __forceinline__ unsigned cvt_pk_bf16(float lo, float hi) { unsigned r; asm volatile("v_cvt_pk_bf16_f32 %0, %1, %2" : "=v"(r) : "v"(lo), "v"(hi)); return r; }
; __device__ __forceinline__ float silu_f(float a) { return a * __builtin_amdgcn_rcpf(1.0f + __expf(-a)); }
;     __device__ __forceinline__ void operator()(const f32x4 (&acc)[2][2][4][2], const pg8::Unit& u, int wr, int wc, int fr, int fq) const {
;     ...
;             for (int ai = 0; ai < 2; ++ai) {
;                 const int chunk = u.pm * 4 + ai * 2 + wr;
;                 const int cseq = lat ? (chunk & 63) : ((chunk - MLAT / 64) & 3);
;                 const bool seq_first = cseq == 0, seq_last = lat ? (cseq == 63) : (cseq == 3);
;                 const int fb = u.pn * 128 + wc * 32 + 8 * fq;
;                 u32x2 uw0[4];
; #pragma unroll
;                 for (int n = 0; n < 2; ++n) {
;                     const int f0 = fb + 4 * n;
;                     const f32x4 w0 = *(const f32x4*)(cw + f0), w1 = *(const f32x4*)(cw + DFF + f0), w2 = *(const f32x4*)(cw + 2 * DFF + f0), bb = *(const f32x4*)(cb + f0);
;                     f32x4 pre[4];
; #pragma unroll
;                     for (int j = 0; j < 4; ++j) {
;                         float t[4], up[4], dn[4];
; #pragma unroll
;                         for (int m = 0; m < 4; ++m) { t[m] = acc[ai][0][m][n][j];
;                             up[m] = __builtin_bit_cast(float, __builtin_amdgcn_update_dpp(0, __builtin_bit_cast(int, t[m]), 0x121, 0xf, 0xf, false));
;                             dn[m] = __builtin_bit_cast(float, __builtin_amdgcn_update_dpp(0, __builtin_bit_cast(int, t[m]), 0x12F, 0xf, 0xf, false)); }
;     ...
;                         u32x2 w; w.x = cvt_pk_bf16(silu_f(pre[m][0]) * vv[0], silu_f(pre[m][1]) * vv[1]); w.y = cvt_pk_bf16(silu_f(pre[m][2]) * vv[2], silu_f(pre[m][3]) * vv[3]);
;                         if (n == 0) uw0[m] = w;
;                         else if (!need_fix) { const int row = rowt + lane_r + ai * 128 + m * 16; *(u32x4*)(U + (size_t)row * DFF + fb) = (u32x4){uw0[m].x, uw0[m].y, w.x, w.y}; }
.Lmy_f1_b01:
	s_mov_b64 exec, s[56:57]
	s_nop 1
	v_pk_mul_f32 v[134:135], v[166:167], s[28:29] op_sel_hi:[1,0]
	v_pk_mul_f32 v[136:137], v[168:169], s[28:29] op_sel_hi:[1,0]
	v_pk_mul_f32 v[126:127], v[170:171], s[28:29] op_sel_hi:[1,0]
	v_pk_mul_f32 v[128:129], v[172:173], s[28:29] op_sel_hi:[1,0]
	v_pk_mul_f32 v[110:111], v[174:175], s[28:29] op_sel_hi:[1,0]
	v_pk_mul_f32 v[112:113], v[176:177], s[28:29] op_sel_hi:[1,0]
	v_pk_mul_f32 v[94:95], v[178:179], s[28:29] op_sel_hi:[1,0]
	v_pk_mul_f32 v[96:97], v[180:181], s[28:29] op_sel_hi:[1,0]
	v_exp_f32_e32 v134, v134
	v_exp_f32_e32 v135, v135
	v_exp_f32_e32 v136, v136
	v_exp_f32_e32 v137, v137
	v_exp_f32_e32 v126, v126
	v_exp_f32_e32 v127, v127
	v_exp_f32_e32 v128, v128
	v_exp_f32_e32 v129, v129
	v_exp_f32_e32 v110, v110
	v_exp_f32_e32 v111, v111
	v_exp_f32_e32 v112, v112
	v_exp_f32_e32 v113, v113
	v_exp_f32_e32 v94, v94
	v_exp_f32_e32 v95, v95
	v_exp_f32_e32 v96, v96
	v_exp_f32_e32 v97, v97
	v_pk_add_f32 v[134:135], v[134:135], 1.0 op_sel_hi:[1,0]
	v_pk_add_f32 v[136:137], v[136:137], 1.0 op_sel_hi:[1,0]
	v_pk_add_f32 v[126:127], v[126:127], 1.0 op_sel_hi:[1,0]
	v_pk_add_f32 v[128:129], v[128:129], 1.0 op_sel_hi:[1,0]
	v_pk_add_f32 v[110:111], v[110:111], 1.0 op_sel_hi:[1,0]
	v_pk_add_f32 v[112:113], v[112:113], 1.0 op_sel_hi:[1,0]
	v_pk_add_f32 v[94:95], v[94:95], 1.0 op_sel_hi:[1,0]
	v_pk_add_f32 v[96:97], v[96:97], 1.0 op_sel_hi:[1,0]
	v_rcp_f32_e32 v134, v134
	v_rcp_f32_e32 v135, v135
	v_rcp_f32_e32 v136, v136
	v_rcp_f32_e32 v137, v137
	v_rcp_f32_e32 v126, v126
	v_rcp_f32_e32 v127, v127
	v_rcp_f32_e32 v128, v128
	v_rcp_f32_e32 v129, v129
	v_rcp_f32_e32 v110, v110
	v_rcp_f32_e32 v111, v111
	v_rcp_f32_e32 v112, v112
	v_rcp_f32_e32 v113, v113
	v_rcp_f32_e32 v94, v94
	v_rcp_f32_e32 v95, v95
	v_rcp_f32_e32 v96, v96
	v_rcp_f32_e32 v97, v97
	v_pk_mul_f32 v[166:167], v[166:167], v[134:135]
	v_pk_mul_f32 v[168:169], v[168:169], v[136:137]
	v_pk_mul_f32 v[170:171], v[170:171], v[126:127]
	v_pk_mul_f32 v[172:173], v[172:173], v[128:129]
	v_pk_mul_f32 v[174:175], v[174:175], v[110:111]
	v_pk_mul_f32 v[176:177], v[176:177], v[112:113]
	v_pk_mul_f32 v[178:179], v[178:179], v[94:95]
	v_pk_mul_f32 v[180:181], v[180:181], v[96:97]
	v_pk_mul_f32 v[166:167], v[114:115], v[166:167]
	v_pk_mul_f32 v[168:169], v[116:117], v[168:169]
	v_pk_mul_f32 v[170:171], v[98:99], v[170:171]
	v_pk_mul_f32 v[172:173], v[100:101], v[172:173]
	v_pk_mul_f32 v[174:175], v[86:87], v[174:175]
	v_pk_mul_f32 v[176:177], v[88:89], v[176:177]
	v_pk_mul_f32 v[178:179], v[78:79], v[178:179]
	v_pk_mul_f32 v[180:181], v[80:81], v[180:181]
	v_cvt_pk_bf16_f32 v124, v166, v167
	v_cvt_pk_bf16_f32 v125, v168, v169
	v_cvt_pk_bf16_f32 v108, v170, v171
	v_cvt_pk_bf16_f32 v109, v172, v173
	v_cvt_pk_bf16_f32 v92, v174, v175
	v_cvt_pk_bf16_f32 v93, v176, v177
	v_cvt_pk_bf16_f32 v84, v178, v179
	v_cvt_pk_bf16_f32 v85, v180, v181
	s_mov_b64 s[0:1], s[44:45]
	s_bitcmp1_b32 s27, 0
	s_cbranch_scc0 .Lmy_f1_u00
	s_andn2_b64 exec, s[56:57], s[42:43]
.Lmy_f1_u00:
	global_store_dwordx4 v204, v[122:125], s[0:1]
	s_mov_b64 exec, s[56:57]
	s_add_u32 s0, s44, 0x16000
	s_addc_u32 s1, s45, 0
	global_store_dwordx4 v204, v[106:109], s[0:1]
	s_add_u32 s0, s44, 0x2c000
	s_addc_u32 s1, s45, 0
	global_store_dwordx4 v204, v[90:93], s[0:1]
	s_add_u32 s0, s44, 0x42000
	s_addc_u32 s1, s45, 0
	s_bitcmp1_b32 s27, 1
	s_cbranch_scc0 .Lmy_f1_u03
	s_andn2_b64 exec, s[56:57], s[40:41]
.Lmy_f1_u03:
	global_store_dwordx4 v204, v[82:85], s[0:1]
	s_mov_b64 exec, s[56:57]
	s_add_i32 s1, s51, 2
	s_and_b32 s0, s1, s25
	s_cmp_lg_u32 s0, 0
	s_cselect_b32 s27, 1, 0
	s_cmp_lg_u32 s0, s25
	s_cselect_b32 s0, 2, 0
	s_or_b32 s27, s27, s0
	s_lshl_b32 s1, s1, 1
	s_mul_i32 s1, s1, 0x8400
	s_add_u32 s30, s66, s1
	s_addc_u32 s31, s67, 0
	v_pk_fma_f32 v[166:167], v[146:147], v[74:75], v[154:155]
	v_pk_fma_f32 v[168:169], v[148:149], v[76:77], v[156:157]
	v_pk_fma_f32 v[170:171], v[146:147], v[66:67], v[154:155]
	v_pk_fma_f32 v[172:173], v[148:149], v[68:69], v[156:157]
	v_pk_fma_f32 v[174:175], v[146:147], v[50:51], v[154:155]
	v_pk_fma_f32 v[176:177], v[148:149], v[52:53], v[156:157]
	v_pk_fma_f32 v[178:179], v[146:147], v[34:35], v[154:155]
	v_pk_fma_f32 v[180:181], v[148:149], v[36:37], v[156:157]
	v_fmac_f32_dpp v166, v74, v142 row_shr:1 row_mask:0xf bank_mask:0xf bound_ctrl:0
	v_fmac_f32_dpp v167, v75, v143 row_shr:1 row_mask:0xf bank_mask:0xf bound_ctrl:0
	v_fmac_f32_dpp v168, v76, v144 row_shr:1 row_mask:0xf bank_mask:0xf bound_ctrl:0
	v_fmac_f32_dpp v169, v77, v145 row_shr:1 row_mask:0xf bank_mask:0xf bound_ctrl:0
	v_fmac_f32_dpp v170, v66, v142 row_shr:1 row_mask:0xf bank_mask:0xf bound_ctrl:0
	v_fmac_f32_dpp v171, v67, v143 row_shr:1 row_mask:0xf bank_mask:0xf bound_ctrl:0
	v_fmac_f32_dpp v172, v68, v144 row_shr:1 row_mask:0xf bank_mask:0xf bound_ctrl:0
	v_fmac_f32_dpp v173, v69, v145 row_shr:1 row_mask:0xf bank_mask:0xf bound_ctrl:0
	v_fmac_f32_dpp v174, v50, v142 row_shr:1 row_mask:0xf bank_mask:0xf bound_ctrl:0
	v_fmac_f32_dpp v175, v51, v143 row_shr:1 row_mask:0xf bank_mask:0xf bound_ctrl:0
	v_fmac_f32_dpp v176, v52, v144 row_shr:1 row_mask:0xf bank_mask:0xf bound_ctrl:0
	v_fmac_f32_dpp v177, v53, v145 row_shr:1 row_mask:0xf bank_mask:0xf bound_ctrl:0
	v_fmac_f32_dpp v178, v34, v142 row_shr:1 row_mask:0xf bank_mask:0xf bound_ctrl:0
	v_fmac_f32_dpp v179, v35, v143 row_shr:1 row_mask:0xf bank_mask:0xf bound_ctrl:0
	v_fmac_f32_dpp v180, v36, v144 row_shr:1 row_mask:0xf bank_mask:0xf bound_ctrl:0
	v_fmac_f32_dpp v181, v37, v145 row_shr:1 row_mask:0xf bank_mask:0xf bound_ctrl:0
	v_fmac_f32_dpp v170, v74, v158 row_ror:1 row_mask:0xf bank_mask:0xf
	v_fmac_f32_dpp v171, v75, v159 row_ror:1 row_mask:0xf bank_mask:0xf
; __device__ __forceinline__ unsigned cvt_pk_bf16(float lo, float hi) { unsigned r; asm volatile("v_cvt_pk_bf16_f32 %0, %1, %2" : "=v"(r) : "v"(lo), "v"(hi)); return r; }
; __device__ __forceinline__ float silu_f(float a) { return a * __builtin_amdgcn_rcpf(1.0f + __expf(-a)); }
;     __device__ __forceinline__ void operator()(const f32x4 (&acc)[2][2][4][2], const pg8::Unit& u, int wr, int wc, int fr, int fq) const {
;     ...
;                         for (int m = 0; m < 4; ++m) { t[m] = acc[ai][0][m][n][j];
;                             up[m] = __builtin_bit_cast(float, __builtin_amdgcn_update_dpp(0, __builtin_bit_cast(int, t[m]), 0x121, 0xf, 0xf, false));
;                             dn[m] = __builtin_bit_cast(float, __builtin_amdgcn_update_dpp(0, __builtin_bit_cast(int, t[m]), 0x12F, 0xf, 0xf, false)); }
; #pragma unroll
;                         for (int m = 0; m < 4; ++m) {
;                             const float pv = (fr == 0) ? (m > 0 ? up[m > 0 ? m - 1 : 0] : 0.f) : up[m];
;                             const float nx = (fr == 15) ? (m < 3 ? dn[m < 3 ? m + 1 : 3] : 0.f) : dn[m];
;                             pre[m][j] = w0[j] * pv + w1[j] * t[m] + w2[j] * nx + bb[j];
;                         }
;                     }
; #pragma unroll
;                     for (int m = 0; m < 4; ++m) {
;                         const bool top = (m == 0 && fr == 0), bot = (m == 3 && fr == 15);
;                         const bool need_fix = (top && !seq_first) || (bot && !seq_last);
;                         const f32x4 vv = acc[ai][1][m][n];
;                         if (top || bot) {
;                             float* e = EDGE + ((size_t)(chunk * 2 + (bot ? 1 : 0)) * 3) * DFF + f0;
;                             *(f32x4*)e = acc[ai][0][m][n];
;                             if (need_fix) { *(f32x4*)(e + DFF) = pre[m]; *(f32x4*)(e + 2 * DFF) = vv; }
;                         }
;                         u32x2 w; w.x = cvt_pk_bf16(silu_f(pre[m][0]) * vv[0], silu_f(pre[m][1]) * vv[1]); w.y = cvt_pk_bf16(silu_f(pre[m][2]) * vv[2], silu_f(pre[m][3]) * vv[3]);
	v_fmac_f32_dpp v172, v76, v160 row_ror:1 row_mask:0xf bank_mask:0xf
	v_fmac_f32_dpp v173, v77, v161 row_ror:1 row_mask:0xf bank_mask:0xf
	v_fmac_f32_dpp v174, v66, v158 row_ror:1 row_mask:0xf bank_mask:0xf
	v_fmac_f32_dpp v175, v67, v159 row_ror:1 row_mask:0xf bank_mask:0xf
	v_fmac_f32_dpp v176, v68, v160 row_ror:1 row_mask:0xf bank_mask:0xf
	v_fmac_f32_dpp v177, v69, v161 row_ror:1 row_mask:0xf bank_mask:0xf
	v_fmac_f32_dpp v178, v50, v158 row_ror:1 row_mask:0xf bank_mask:0xf
	v_fmac_f32_dpp v179, v51, v159 row_ror:1 row_mask:0xf bank_mask:0xf
	v_fmac_f32_dpp v180, v52, v160 row_ror:1 row_mask:0xf bank_mask:0xf
	v_fmac_f32_dpp v181, v53, v161 row_ror:1 row_mask:0xf bank_mask:0xf
	v_fmac_f32_dpp v166, v74, v150 row_shl:1 row_mask:0xf bank_mask:0xf bound_ctrl:0
	v_fmac_f32_dpp v167, v75, v151 row_shl:1 row_mask:0xf bank_mask:0xf bound_ctrl:0
	v_fmac_f32_dpp v168, v76, v152 row_shl:1 row_mask:0xf bank_mask:0xf bound_ctrl:0
	v_fmac_f32_dpp v169, v77, v153 row_shl:1 row_mask:0xf bank_mask:0xf bound_ctrl:0
	v_fmac_f32_dpp v170, v66, v150 row_shl:1 row_mask:0xf bank_mask:0xf bound_ctrl:0
	v_fmac_f32_dpp v171, v67, v151 row_shl:1 row_mask:0xf bank_mask:0xf bound_ctrl:0
	v_fmac_f32_dpp v172, v68, v152 row_shl:1 row_mask:0xf bank_mask:0xf bound_ctrl:0
	v_fmac_f32_dpp v173, v69, v153 row_shl:1 row_mask:0xf bank_mask:0xf bound_ctrl:0
	v_fmac_f32_dpp v174, v50, v150 row_shl:1 row_mask:0xf bank_mask:0xf bound_ctrl:0
	v_fmac_f32_dpp v175, v51, v151 row_shl:1 row_mask:0xf bank_mask:0xf bound_ctrl:0
	v_fmac_f32_dpp v176, v52, v152 row_shl:1 row_mask:0xf bank_mask:0xf bound_ctrl:0
	v_fmac_f32_dpp v177, v53, v153 row_shl:1 row_mask:0xf bank_mask:0xf bound_ctrl:0
	v_fmac_f32_dpp v178, v34, v150 row_shl:1 row_mask:0xf bank_mask:0xf bound_ctrl:0
	v_fmac_f32_dpp v179, v35, v151 row_shl:1 row_mask:0xf bank_mask:0xf bound_ctrl:0
	v_fmac_f32_dpp v180, v36, v152 row_shl:1 row_mask:0xf bank_mask:0xf bound_ctrl:0
	v_fmac_f32_dpp v181, v37, v153 row_shl:1 row_mask:0xf bank_mask:0xf bound_ctrl:0
	v_fmac_f32_dpp v166, v66, v162 row_ror:15 row_mask:0xf bank_mask:0xf
	v_fmac_f32_dpp v167, v67, v163 row_ror:15 row_mask:0xf bank_mask:0xf
	v_fmac_f32_dpp v168, v68, v164 row_ror:15 row_mask:0xf bank_mask:0xf
	v_fmac_f32_dpp v169, v69, v165 row_ror:15 row_mask:0xf bank_mask:0xf
	v_fmac_f32_dpp v170, v50, v162 row_ror:15 row_mask:0xf bank_mask:0xf
	v_fmac_f32_dpp v171, v51, v163 row_ror:15 row_mask:0xf bank_mask:0xf
	v_fmac_f32_dpp v172, v52, v164 row_ror:15 row_mask:0xf bank_mask:0xf
	v_fmac_f32_dpp v173, v53, v165 row_ror:15 row_mask:0xf bank_mask:0xf
	v_fmac_f32_dpp v174, v34, v162 row_ror:15 row_mask:0xf bank_mask:0xf
	v_fmac_f32_dpp v175, v35, v163 row_ror:15 row_mask:0xf bank_mask:0xf
	v_fmac_f32_dpp v176, v36, v164 row_ror:15 row_mask:0xf bank_mask:0xf
	v_fmac_f32_dpp v177, v37, v165 row_ror:15 row_mask:0xf bank_mask:0xf
	s_mov_b64 exec, s[42:43]
	global_store_dwordx4 v202, v[74:77], s[30:31]
	s_bitcmp1_b32 s27, 0
	s_cbranch_scc0 .Lmy_f1_t10
	s_add_u32 s0, s30, 0x2c00
	s_addc_u32 s1, s31, 0
	global_store_dwordx4 v202, v[166:169], s[0:1]
	s_add_u32 s0, s0, 0x2c00
	s_addc_u32 s1, s1, 0
	global_store_dwordx4 v202, v[58:61], s[0:1]
.Lmy_f1_t10:
	s_mov_b64 exec, s[40:41]
	s_add_u32 s0, s30, 0x8400
	s_addc_u32 s1, s31, 0
	global_store_dwordx4 v202, v[34:37], s[0:1]
	s_bitcmp1_b32 s27, 1
	s_cbranch_scc0 .Lmy_f1_b10
	s_add_u32 s0, s0, 0x2c00
	s_addc_u32 s1, s1, 0
	global_store_dwordx4 v202, v[178:181], s[0:1]
	s_add_u32 s0, s0, 0x2c00
	s_addc_u32 s1, s1, 0
	global_store_dwordx4 v202, v[18:21], s[0:1]
.Lmy_f1_b10:
	s_mov_b64 exec, s[56:57]
	s_nop 1
	v_pk_mul_f32 v[74:75], v[166:167], s[28:29] op_sel_hi:[1,0]
	v_pk_mul_f32 v[76:77], v[168:169], s[28:29] op_sel_hi:[1,0]
	v_pk_mul_f32 v[66:67], v[170:171], s[28:29] op_sel_hi:[1,0]
	v_pk_mul_f32 v[68:69], v[172:173], s[28:29] op_sel_hi:[1,0]
	v_pk_mul_f32 v[50:51], v[174:175], s[28:29] op_sel_hi:[1,0]
	v_pk_mul_f32 v[52:53], v[176:177], s[28:29] op_sel_hi:[1,0]
	v_pk_mul_f32 v[34:35], v[178:179], s[28:29] op_sel_hi:[1,0]
	v_pk_mul_f32 v[36:37], v[180:181], s[28:29] op_sel_hi:[1,0]
	v_exp_f32_e32 v74, v74
	v_exp_f32_e32 v75, v75
	v_exp_f32_e32 v76, v76
	v_exp_f32_e32 v77, v77
	v_exp_f32_e32 v66, v66
	v_exp_f32_e32 v67, v67
	v_exp_f32_e32 v68, v68
	v_exp_f32_e32 v69, v69
	v_exp_f32_e32 v50, v50
	v_exp_f32_e32 v51, v51
	v_exp_f32_e32 v52, v52
	v_exp_f32_e32 v53, v53
	v_exp_f32_e32 v34, v34
	v_exp_f32_e32 v35, v35
	v_exp_f32_e32 v36, v36
	v_exp_f32_e32 v37, v37
	v_pk_add_f32 v[74:75], v[74:75], 1.0 op_sel_hi:[1,0]
	v_pk_add_f32 v[76:77], v[76:77], 1.0 op_sel_hi:[1,0]
	v_pk_add_f32 v[66:67], v[66:67], 1.0 op_sel_hi:[1,0]
	v_pk_add_f32 v[68:69], v[68:69], 1.0 op_sel_hi:[1,0]
	v_pk_add_f32 v[50:51], v[50:51], 1.0 op_sel_hi:[1,0]
	v_pk_add_f32 v[52:53], v[52:53], 1.0 op_sel_hi:[1,0]
	v_pk_add_f32 v[34:35], v[34:35], 1.0 op_sel_hi:[1,0]
	v_pk_add_f32 v[36:37], v[36:37], 1.0 op_sel_hi:[1,0]
	v_rcp_f32_e32 v74, v74
	v_rcp_f32_e32 v75, v75
	v_rcp_f32_e32 v76, v76
	v_rcp_f32_e32 v77, v77
	v_rcp_f32_e32 v66, v66
	v_rcp_f32_e32 v67, v67
	v_rcp_f32_e32 v68, v68
	v_rcp_f32_e32 v69, v69
	v_rcp_f32_e32 v50, v50
	v_rcp_f32_e32 v51, v51
	v_rcp_f32_e32 v52, v52
	v_rcp_f32_e32 v53, v53
	v_rcp_f32_e32 v34, v34
	v_rcp_f32_e32 v35, v35
	v_rcp_f32_e32 v36, v36
	v_rcp_f32_e32 v37, v37
	v_pk_mul_f32 v[166:167], v[166:167], v[74:75]
	v_pk_mul_f32 v[168:169], v[168:169], v[76:77]
	v_pk_mul_f32 v[170:171], v[170:171], v[66:67]
	v_pk_mul_f32 v[172:173], v[172:173], v[68:69]
	v_pk_mul_f32 v[174:175], v[174:175], v[50:51]
	v_pk_mul_f32 v[176:177], v[176:177], v[52:53]
	v_pk_mul_f32 v[178:179], v[178:179], v[34:35]
	v_pk_mul_f32 v[180:181], v[180:181], v[36:37]
;     __device__ __forceinline__ void operator()(const f32x4 (&acc)[2][2][4][2], const pg8::Unit& u, int wr, int wc, int fr, int fq) const {
;     ...
;                     for (int j = 0; j < 4; ++j) {
;                         float t[4], up[4], dn[4];
; #pragma unroll
;                         for (int m = 0; m < 4; ++m) { t[m] = acc[ai][0][m][n][j];
;                             up[m] = __builtin_bit_cast(float, __builtin_amdgcn_update_dpp(0, __builtin_bit_cast(int, t[m]), 0x121, 0xf, 0xf, false));
;                             dn[m] = __builtin_bit_cast(float, __builtin_amdgcn_update_dpp(0, __builtin_bit_cast(int, t[m]), 0x12F, 0xf, 0xf, false)); }
; #pragma unroll
;                         for (int m = 0; m < 4; ++m) {
;                             const float pv = (fr == 0) ? (m > 0 ? up[m > 0 ? m - 1 : 0] : 0.f) : up[m];
;                             const float nx = (fr == 15) ? (m < 3 ? dn[m < 3 ? m + 1 : 3] : 0.f) : dn[m];
;                             pre[m][j] = w0[j] * pv + w1[j] * t[m] + w2[j] * nx + bb[j];
;                         }
;                     }
; #pragma unroll
;                     for (int m = 0; m < 4; ++m) {
;                         const bool top = (m == 0 && fr == 0), bot = (m == 3 && fr == 15);
;                         const bool need_fix = (top && !seq_first) || (bot && !seq_last);
;                         const f32x4 vv = acc[ai][1][m][n];
;                         if (top || bot) {
;                             float* e = EDGE + ((size_t)(chunk * 2 + (bot ? 1 : 0)) * 3) * DFF + f0;
;                             *(f32x4*)e = acc[ai][0][m][n];
;                             if (need_fix) { *(f32x4*)(e + DFF) = pre[m]; *(f32x4*)(e + 2 * DFF) = vv; }
;                         }
	v_pk_mul_f32 v[166:167], v[58:59], v[166:167]
	v_pk_mul_f32 v[168:169], v[60:61], v[168:169]
	v_pk_mul_f32 v[170:171], v[42:43], v[170:171]
	v_pk_mul_f32 v[172:173], v[44:45], v[172:173]
	v_pk_mul_f32 v[174:175], v[26:27], v[174:175]
	v_pk_mul_f32 v[176:177], v[28:29], v[176:177]
	v_pk_mul_f32 v[178:179], v[18:19], v[178:179]
	v_pk_mul_f32 v[180:181], v[20:21], v[180:181]
	v_cvt_pk_bf16_f32 v58, v166, v167
	v_cvt_pk_bf16_f32 v59, v168, v169
	v_cvt_pk_bf16_f32 v42, v170, v171
	v_cvt_pk_bf16_f32 v43, v172, v173
	v_cvt_pk_bf16_f32 v26, v174, v175
	v_cvt_pk_bf16_f32 v27, v176, v177
	v_cvt_pk_bf16_f32 v18, v178, v179
	v_cvt_pk_bf16_f32 v19, v180, v181
	v_pk_fma_f32 v[166:167], v[226:227], v[70:71], v[234:235]
	v_pk_fma_f32 v[168:169], v[228:229], v[72:73], v[236:237]
	v_pk_fma_f32 v[170:171], v[226:227], v[62:63], v[234:235]
	v_pk_fma_f32 v[172:173], v[228:229], v[64:65], v[236:237]
	v_pk_fma_f32 v[174:175], v[226:227], v[46:47], v[234:235]
	v_pk_fma_f32 v[176:177], v[228:229], v[48:49], v[236:237]
	v_pk_fma_f32 v[178:179], v[226:227], v[30:31], v[234:235]
	v_pk_fma_f32 v[180:181], v[228:229], v[32:33], v[236:237]
	v_fmac_f32_dpp v166, v70, v222 row_shr:1 row_mask:0xf bank_mask:0xf bound_ctrl:0
	v_fmac_f32_dpp v167, v71, v223 row_shr:1 row_mask:0xf bank_mask:0xf bound_ctrl:0
	v_fmac_f32_dpp v168, v72, v224 row_shr:1 row_mask:0xf bank_mask:0xf bound_ctrl:0
	v_fmac_f32_dpp v169, v73, v225 row_shr:1 row_mask:0xf bank_mask:0xf bound_ctrl:0
	v_fmac_f32_dpp v170, v62, v222 row_shr:1 row_mask:0xf bank_mask:0xf bound_ctrl:0
	v_fmac_f32_dpp v171, v63, v223 row_shr:1 row_mask:0xf bank_mask:0xf bound_ctrl:0
	v_fmac_f32_dpp v172, v64, v224 row_shr:1 row_mask:0xf bank_mask:0xf bound_ctrl:0
	v_fmac_f32_dpp v173, v65, v225 row_shr:1 row_mask:0xf bank_mask:0xf bound_ctrl:0
	v_fmac_f32_dpp v174, v46, v222 row_shr:1 row_mask:0xf bank_mask:0xf bound_ctrl:0
	v_fmac_f32_dpp v175, v47, v223 row_shr:1 row_mask:0xf bank_mask:0xf bound_ctrl:0
	v_fmac_f32_dpp v176, v48, v224 row_shr:1 row_mask:0xf bank_mask:0xf bound_ctrl:0
	v_fmac_f32_dpp v177, v49, v225 row_shr:1 row_mask:0xf bank_mask:0xf bound_ctrl:0
	v_fmac_f32_dpp v178, v30, v222 row_shr:1 row_mask:0xf bank_mask:0xf bound_ctrl:0
	v_fmac_f32_dpp v179, v31, v223 row_shr:1 row_mask:0xf bank_mask:0xf bound_ctrl:0
	v_fmac_f32_dpp v180, v32, v224 row_shr:1 row_mask:0xf bank_mask:0xf bound_ctrl:0
	v_fmac_f32_dpp v181, v33, v225 row_shr:1 row_mask:0xf bank_mask:0xf bound_ctrl:0
	v_fmac_f32_dpp v170, v70, v238 row_ror:1 row_mask:0xf bank_mask:0xf
	v_fmac_f32_dpp v171, v71, v239 row_ror:1 row_mask:0xf bank_mask:0xf
	v_fmac_f32_dpp v172, v72, v240 row_ror:1 row_mask:0xf bank_mask:0xf
	v_fmac_f32_dpp v173, v73, v241 row_ror:1 row_mask:0xf bank_mask:0xf
	v_fmac_f32_dpp v174, v62, v238 row_ror:1 row_mask:0xf bank_mask:0xf
	v_fmac_f32_dpp v175, v63, v239 row_ror:1 row_mask:0xf bank_mask:0xf
	v_fmac_f32_dpp v176, v64, v240 row_ror:1 row_mask:0xf bank_mask:0xf
	v_fmac_f32_dpp v177, v65, v241 row_ror:1 row_mask:0xf bank_mask:0xf
	v_fmac_f32_dpp v178, v46, v238 row_ror:1 row_mask:0xf bank_mask:0xf
	v_fmac_f32_dpp v179, v47, v239 row_ror:1 row_mask:0xf bank_mask:0xf
	v_fmac_f32_dpp v180, v48, v240 row_ror:1 row_mask:0xf bank_mask:0xf
	v_fmac_f32_dpp v181, v49, v241 row_ror:1 row_mask:0xf bank_mask:0xf
	v_fmac_f32_dpp v166, v70, v230 row_shl:1 row_mask:0xf bank_mask:0xf bound_ctrl:0
	v_fmac_f32_dpp v167, v71, v231 row_shl:1 row_mask:0xf bank_mask:0xf bound_ctrl:0
	v_fmac_f32_dpp v168, v72, v232 row_shl:1 row_mask:0xf bank_mask:0xf bound_ctrl:0
	v_fmac_f32_dpp v169, v73, v233 row_shl:1 row_mask:0xf bank_mask:0xf bound_ctrl:0
	v_fmac_f32_dpp v170, v62, v230 row_shl:1 row_mask:0xf bank_mask:0xf bound_ctrl:0
	v_fmac_f32_dpp v171, v63, v231 row_shl:1 row_mask:0xf bank_mask:0xf bound_ctrl:0
	v_fmac_f32_dpp v172, v64, v232 row_shl:1 row_mask:0xf bank_mask:0xf bound_ctrl:0
	v_fmac_f32_dpp v173, v65, v233 row_shl:1 row_mask:0xf bank_mask:0xf bound_ctrl:0
	v_fmac_f32_dpp v174, v46, v230 row_shl:1 row_mask:0xf bank_mask:0xf bound_ctrl:0
	v_fmac_f32_dpp v175, v47, v231 row_shl:1 row_mask:0xf bank_mask:0xf bound_ctrl:0
	v_fmac_f32_dpp v176, v48, v232 row_shl:1 row_mask:0xf bank_mask:0xf bound_ctrl:0
	v_fmac_f32_dpp v177, v49, v233 row_shl:1 row_mask:0xf bank_mask:0xf bound_ctrl:0
	v_fmac_f32_dpp v178, v30, v230 row_shl:1 row_mask:0xf bank_mask:0xf bound_ctrl:0
	v_fmac_f32_dpp v179, v31, v231 row_shl:1 row_mask:0xf bank_mask:0xf bound_ctrl:0
	v_fmac_f32_dpp v180, v32, v232 row_shl:1 row_mask:0xf bank_mask:0xf bound_ctrl:0
	v_fmac_f32_dpp v181, v33, v233 row_shl:1 row_mask:0xf bank_mask:0xf bound_ctrl:0
	v_fmac_f32_dpp v166, v62, v198 row_ror:15 row_mask:0xf bank_mask:0xf
	v_fmac_f32_dpp v167, v63, v199 row_ror:15 row_mask:0xf bank_mask:0xf
	v_fmac_f32_dpp v168, v64, v200 row_ror:15 row_mask:0xf bank_mask:0xf
	v_fmac_f32_dpp v169, v65, v201 row_ror:15 row_mask:0xf bank_mask:0xf
	v_fmac_f32_dpp v170, v46, v198 row_ror:15 row_mask:0xf bank_mask:0xf
	v_fmac_f32_dpp v171, v47, v199 row_ror:15 row_mask:0xf bank_mask:0xf
	v_fmac_f32_dpp v172, v48, v200 row_ror:15 row_mask:0xf bank_mask:0xf
	v_fmac_f32_dpp v173, v49, v201 row_ror:15 row_mask:0xf bank_mask:0xf
	v_fmac_f32_dpp v174, v30, v198 row_ror:15 row_mask:0xf bank_mask:0xf
	v_fmac_f32_dpp v175, v31, v199 row_ror:15 row_mask:0xf bank_mask:0xf
	v_fmac_f32_dpp v176, v32, v200 row_ror:15 row_mask:0xf bank_mask:0xf
	v_fmac_f32_dpp v177, v33, v201 row_ror:15 row_mask:0xf bank_mask:0xf
	s_mov_b64 exec, s[42:43]
	global_store_dwordx4 v203, v[70:73], s[30:31]
	s_bitcmp1_b32 s27, 0
	s_cbranch_scc0 .Lmy_f1_t11
	s_add_u32 s0, s30, 0x2c00
	s_addc_u32 s1, s31, 0
	global_store_dwordx4 v203, v[166:169], s[0:1]
	s_add_u32 s0, s0, 0x2c00
	s_addc_u32 s1, s1, 0
	global_store_dwordx4 v203, v[54:57], s[0:1]
; __device__ __forceinline__ unsigned cvt_pk_bf16(float lo, float hi) { unsigned r; asm volatile("v_cvt_pk_bf16_f32 %0, %1, %2" : "=v"(r) : "v"(lo), "v"(hi)); return r; }
; __device__ __forceinline__ float silu_f(float a) { return a * __builtin_amdgcn_rcpf(1.0f + __expf(-a)); }
;     __device__ __forceinline__ void operator()(const f32x4 (&acc)[2][2][4][2], const pg8::Unit& u, int wr, int wc, int fr, int fq) const {
;     ...
;                     for (int m = 0; m < 4; ++m) {
;                         const bool top = (m == 0 && fr == 0), bot = (m == 3 && fr == 15);
;                         const bool need_fix = (top && !seq_first) || (bot && !seq_last);
;                         const f32x4 vv = acc[ai][1][m][n];
;                         if (top || bot) {
;                             float* e = EDGE + ((size_t)(chunk * 2 + (bot ? 1 : 0)) * 3) * DFF + f0;
;                             *(f32x4*)e = acc[ai][0][m][n];
;                             if (need_fix) { *(f32x4*)(e + DFF) = pre[m]; *(f32x4*)(e + 2 * DFF) = vv; }
;                         }
;                         u32x2 w; w.x = cvt_pk_bf16(silu_f(pre[m][0]) * vv[0], silu_f(pre[m][1]) * vv[1]); w.y = cvt_pk_bf16(silu_f(pre[m][2]) * vv[2], silu_f(pre[m][3]) * vv[3]);
;                         if (n == 0) uw0[m] = w;
;                         else if (!need_fix) { const int row = rowt + lane_r + ai * 128 + m * 16; *(u32x4*)(U + (size_t)row * DFF + fb) = (u32x4){uw0[m].x, uw0[m].y, w.x, w.y}; }
.Lmy_f1_t11:
	s_mov_b64 exec, s[40:41]
	s_add_u32 s0, s30, 0x8400
	s_addc_u32 s1, s31, 0
	global_store_dwordx4 v203, v[30:33], s[0:1]
	s_bitcmp1_b32 s27, 1
	s_cbranch_scc0 .Lmy_f1_b11
	s_add_u32 s0, s0, 0x2c00
	s_addc_u32 s1, s1, 0
	global_store_dwordx4 v203, v[178:181], s[0:1]
	s_add_u32 s0, s0, 0x2c00
	s_addc_u32 s1, s1, 0
	global_store_dwordx4 v203, v[14:17], s[0:1]
.Lmy_f1_b11:
	s_mov_b64 exec, s[56:57]
	s_nop 1
	v_pk_mul_f32 v[70:71], v[166:167], s[28:29] op_sel_hi:[1,0]
	v_pk_mul_f32 v[72:73], v[168:169], s[28:29] op_sel_hi:[1,0]
	v_pk_mul_f32 v[62:63], v[170:171], s[28:29] op_sel_hi:[1,0]
	v_pk_mul_f32 v[64:65], v[172:173], s[28:29] op_sel_hi:[1,0]
	v_pk_mul_f32 v[46:47], v[174:175], s[28:29] op_sel_hi:[1,0]
	v_pk_mul_f32 v[48:49], v[176:177], s[28:29] op_sel_hi:[1,0]
	v_pk_mul_f32 v[30:31], v[178:179], s[28:29] op_sel_hi:[1,0]
	v_pk_mul_f32 v[32:33], v[180:181], s[28:29] op_sel_hi:[1,0]
	v_exp_f32_e32 v70, v70
	v_exp_f32_e32 v71, v71
	v_exp_f32_e32 v72, v72
	v_exp_f32_e32 v73, v73
	v_exp_f32_e32 v62, v62
	v_exp_f32_e32 v63, v63
	v_exp_f32_e32 v64, v64
	v_exp_f32_e32 v65, v65
	v_exp_f32_e32 v46, v46
	v_exp_f32_e32 v47, v47
	v_exp_f32_e32 v48, v48
	v_exp_f32_e32 v49, v49
	v_exp_f32_e32 v30, v30
	v_exp_f32_e32 v31, v31
	v_exp_f32_e32 v32, v32
	v_exp_f32_e32 v33, v33
	v_pk_add_f32 v[70:71], v[70:71], 1.0 op_sel_hi:[1,0]
	v_pk_add_f32 v[72:73], v[72:73], 1.0 op_sel_hi:[1,0]
	v_pk_add_f32 v[62:63], v[62:63], 1.0 op_sel_hi:[1,0]
	v_pk_add_f32 v[64:65], v[64:65], 1.0 op_sel_hi:[1,0]
	v_pk_add_f32 v[46:47], v[46:47], 1.0 op_sel_hi:[1,0]
	v_pk_add_f32 v[48:49], v[48:49], 1.0 op_sel_hi:[1,0]
	v_pk_add_f32 v[30:31], v[30:31], 1.0 op_sel_hi:[1,0]
	v_pk_add_f32 v[32:33], v[32:33], 1.0 op_sel_hi:[1,0]
	v_rcp_f32_e32 v70, v70
	v_rcp_f32_e32 v71, v71
	v_rcp_f32_e32 v72, v72
	v_rcp_f32_e32 v73, v73
	v_rcp_f32_e32 v62, v62
	v_rcp_f32_e32 v63, v63
	v_rcp_f32_e32 v64, v64
	v_rcp_f32_e32 v65, v65
	v_rcp_f32_e32 v46, v46
	v_rcp_f32_e32 v47, v47
	v_rcp_f32_e32 v48, v48
	v_rcp_f32_e32 v49, v49
	v_rcp_f32_e32 v30, v30
	v_rcp_f32_e32 v31, v31
	v_rcp_f32_e32 v32, v32
	v_rcp_f32_e32 v33, v33
	v_pk_mul_f32 v[166:167], v[166:167], v[70:71]
	v_pk_mul_f32 v[168:169], v[168:169], v[72:73]
	v_pk_mul_f32 v[170:171], v[170:171], v[62:63]
	v_pk_mul_f32 v[172:173], v[172:173], v[64:65]
	v_pk_mul_f32 v[174:175], v[174:175], v[46:47]
	v_pk_mul_f32 v[176:177], v[176:177], v[48:49]
	v_pk_mul_f32 v[178:179], v[178:179], v[30:31]
	v_pk_mul_f32 v[180:181], v[180:181], v[32:33]
	v_pk_mul_f32 v[166:167], v[54:55], v[166:167]
	v_pk_mul_f32 v[168:169], v[56:57], v[168:169]
	v_pk_mul_f32 v[170:171], v[38:39], v[170:171]
	v_pk_mul_f32 v[172:173], v[40:41], v[172:173]
	v_pk_mul_f32 v[174:175], v[22:23], v[174:175]
	v_pk_mul_f32 v[176:177], v[24:25], v[176:177]
	v_pk_mul_f32 v[178:179], v[14:15], v[178:179]
	v_pk_mul_f32 v[180:181], v[16:17], v[180:181]
	v_cvt_pk_bf16_f32 v60, v166, v167
	v_cvt_pk_bf16_f32 v61, v168, v169
	v_cvt_pk_bf16_f32 v44, v170, v171
	v_cvt_pk_bf16_f32 v45, v172, v173
	v_cvt_pk_bf16_f32 v28, v174, v175
	v_cvt_pk_bf16_f32 v29, v176, v177
	v_cvt_pk_bf16_f32 v20, v178, v179
	v_cvt_pk_bf16_f32 v21, v180, v181
	s_add_u32 s0, s44, 0xb0000
	s_addc_u32 s1, s45, 0
	s_bitcmp1_b32 s27, 0
	s_cbranch_scc0 .Lmy_f1_u10
	s_andn2_b64 exec, s[56:57], s[42:43]
.Lmy_f1_u10:
	global_store_dwordx4 v204, v[58:61], s[0:1]
	s_mov_b64 exec, s[56:57]
	s_add_u32 s0, s44, 0xc6000
	s_addc_u32 s1, s45, 0
	global_store_dwordx4 v204, v[42:45], s[0:1]
	s_add_u32 s0, s44, 0xdc000
	s_addc_u32 s1, s45, 0
	global_store_dwordx4 v204, v[26:29], s[0:1]
	s_add_u32 s0, s44, 0xf2000
	s_addc_u32 s1, s45, 0
	s_bitcmp1_b32 s27, 1
	s_cbranch_scc0 .Lmy_f1_u13
	s_andn2_b64 exec, s[56:57], s[40:41]
.Lmy_f1_u13:
	global_store_dwordx4 v204, v[18:21], s[0:1]
	s_mov_b64 exec, s[56:57]
	v_readlane_b32 s56, v249, 0
	v_readlane_b32 s57, v249, 1
	s_nop 1
	s_branch .LBB0_848
